# grid barrier: 8th-from-last arriving workgroup per XCD issues an extra un-waited buffer_wbl2 before polling (leader write-back unchanged)
# baseline (speedup 1.0000x reference)
; __device__ __forceinline__ unsigned xb_ld(unsigned* p)              { return __hip_atomic_load(p, __ATOMIC_RELAXED, __HIP_MEMORY_SCOPE_AGENT); }
; __device__ __forceinline__ unsigned xb_add(unsigned* p, unsigned v) { return __hip_atomic_fetch_add(p, v, __ATOMIC_RELAXED, __HIP_MEMORY_SCOPE_AGENT); }
; #define XB_SPIN(cond, bar) do { unsigned _sp = 0; while (cond) { __builtin_amdgcn_s_sleep(1); \
;     if ((++_sp & 255u) == 0u) { if (xb_ld(&(bar)[XB_TMO])) break; if (_sp > XB_SPIN_CAP) { atomicAdd(&(bar)[XB_TMO], 1u); break; } } } } while (0)
; __device__ __forceinline__ void xcd_barrier(const XcdBarrier& b) {
;     ...
;         const unsigned old = xb_add(&bar[XB_XSUB(b.x)], 1u);
;         const unsigned gen = old / nloc;
;         if (old + 1u == (gen + 1u) * nloc) {
;             __builtin_amdgcn_fence(__ATOMIC_RELEASE, "agent");
;             asm volatile("s_waitcnt vmcnt(0)" ::: "memory");
;             const unsigned og = xb_add(&bar[XB_TOP], 1u);
;             const unsigned tg = og / nx;
;             if (og + 1u == (tg + 1u) * nx) xb_add(&bar[XB_TOPGEN], 1u);
;             else XB_SPIN(xb_ld(&bar[XB_TOPGEN]) == tg, bar);
;             __builtin_amdgcn_fence(__ATOMIC_ACQUIRE, "agent");
;             xb_add(&bar[XB_XGEN(b.x)], 1u);
;             asm volatile("s_waitcnt vmcnt(0)" ::: "memory");
;         } else {
;             XB_SPIN(xb_ld(&bar[XB_TOPGEN]) == gen, bar);
.LBB0_148:
	s_or_b64 exec, exec, s[14:15]
	v_cvt_f32_u32_e32 v4, v2
	s_waitcnt vmcnt(0)
	v_readfirstlane_b32 s3, v3
	v_sub_u32_e32 v3, 0, v2
	v_rcp_iflag_f32_e32 v4, v4
	v_add_u32_e32 v5, s3, v1
	v_mul_f32_e32 v4, 0x4f7ffffe, v4
	v_cvt_u32_f32_e32 v4, v4
	v_mul_lo_u32 v1, v3, v4
	v_mul_hi_u32 v1, v4, v1
	v_add_u32_e32 v1, v4, v1
	v_mul_hi_u32 v1, v5, v1
	v_mul_lo_u32 v3, v1, v2
	v_sub_u32_e32 v3, v5, v3
	v_add_u32_e32 v4, 1, v1
	v_cmp_ge_u32_e32 vcc, v3, v2
	s_nop 1
	v_cndmask_b32_e32 v1, v1, v4, vcc
	v_sub_u32_e32 v4, v3, v2
	v_cndmask_b32_e32 v3, v3, v4, vcc
	v_add_u32_e32 v4, 1, v1
	v_cmp_ge_u32_e32 vcc, v3, v2
	v_add_u32_e32 v3, 1, v5
	s_nop 0
	v_cndmask_b32_e32 v1, v1, v4, vcc
	v_mul_lo_u32 v4, v2, v1
	v_add_u32_e32 v2, v4, v2
	v_cmp_ne_u32_e32 vcc, v3, v2
	s_and_saveexec_b64 s[12:13], vcc
	s_xor_b64 s[12:13], exec, s[12:13]
	s_cbranch_execz .LBB0_162
	s_waitcnt lgkmcnt(0)
	v_add_u32_e32 v6, 8, v5
	v_cmp_eq_u32_e32 vcc, v6, v2
	s_cbranch_vccz .Lxb_nf10
	buffer_wbl2 sc1
.Lxb_nf10:
	v_mov_b32_e32 v0, 0x4000
	global_load_dword v0, v0, s[80:81] offset:1280 sc1
	s_add_u32 s18, s80, 0x4500
	s_addc_u32 s19, s81, 0
	s_waitcnt vmcnt(0)
	v_cmp_eq_u32_e32 vcc, v0, v1
	s_and_saveexec_b64 s[14:15], vcc
	s_cbranch_execz .LBB0_161
	s_add_u32 s16, s80, 0x1200
	s_addc_u32 s17, s81, 0
	s_mov_b32 s3, 1
	s_mov_b64 s[20:21], 0
	v_mov_b32_e32 v0, 0
	s_branch .LBB0_152
